# peeled first K-iteration of all three GEMM K-loops: first-touch MFMAs use C=0, the 62 v_mov_b64 accumulator re-zeroing per tile deleted (on top of nt weight loads, permlane, saddr, EpiVT wait fix)
# speedup vs baseline: 1.0118x; 1.0118x over previous
.LBB0_452:
	s_ashr_i32 s99, s98, 31
	s_lshl_b64 s[28:29], s[98:99], 11
	s_add_u32 s94, s46, s28
	s_addc_u32 s95, s47, s29
	s_and_b64 s[28:29], s[20:21], exec
	s_cselect_b32 s30, s95, s23
	s_cselect_b32 s31, s94, s22
	s_ashr_i32 s81, s80, 31
	s_lshl_b64 s[28:29], s[80:81], 11
	v_readlane_b32 s62, v254, 3
	s_add_u32 s62, s62, s28
	v_readlane_b32 s28, v254, 4
	s_addc_u32 s63, s28, s29
	s_and_b64 s[28:29], s[20:21], exec
	s_cselect_b32 s69, s63, s25
	s_cselect_b32 s75, s62, s24
	s_add_u32 s22, s22, 0x40080
	s_addc_u32 s23, s23, 0
	s_add_u32 s81, s24, 0x100
	s_addc_u32 s99, s25, 0
	s_mov_b32 vcc_lo, -2
	s_add_u32 s24, s22, 0xfffc0080
	s_addc_u32 s25, s23, -1
	s_add_i32 s76, 0, 0x10000
	s_cmp_eq_u32 vcc_lo, 12
	s_cselect_b32 s29, s30, s25
	s_cselect_b32 s28, s31, s24
	v_add_u32_e32 v114, s76, v220
	s_cselect_b32 s25, s69, s99
	s_cselect_b32 s24, s75, s81
	s_add_i32 vcc_hi, 0, 0x14000
	ds_read_b128 v[106:109], v114
	ds_read_b128 v[110:113], v114 offset:1024
	ds_read_b128 v[128:131], v114 offset:2048
	ds_read_b128 v[132:135], v114 offset:3072
	v_add_u32_e32 v114, vcc_hi, v220
	ds_read_b128 v[136:139], v114
	ds_read_b128 v[158:161], v114 offset:1024
	ds_read_b128 v[162:165], v114 offset:2048
	ds_read_b128 v[166:169], v114 offset:3072
	s_add_i32 m0, s57, 0xc000
	ds_read_b128 v[170:173], v234
	ds_read_b128 v[174:177], v234 offset:1024
	ds_read_b128 v[178:181], v234 offset:2048
	ds_read_b128 v[198:201], v234 offset:3072
	ds_read_b128 v[202:205], v234 offset:4096
	ds_read_b128 v[206:209], v234 offset:5120
	ds_read_b128 v[210:213], v234 offset:6144
	ds_read_b128 v[214:217], v234 offset:7168
	global_load_lds_dwordx4 v194, s[22:23]
	s_add_i32 m0, s57, 0xe000
	s_nop 0
	global_load_lds_dwordx4 v196, s[22:23]
	s_waitcnt vmcnt(8)
	s_waitcnt lgkmcnt(0)
	s_barrier
	s_setprio 1
	v_mfma_f32_16x16x32_bf16 v[124:127], v[106:109], v[170:173], 0
	v_mfma_f32_16x16x32_bf16 v[98:101], v[128:131], v[170:173], 0
	v_mfma_f32_16x16x32_bf16 v[154:157], v[106:109], v[178:181], 0
	v_mfma_f32_16x16x32_bf16 v[58:61], v[128:131], v[178:181], 0
	v_mfma_f32_16x16x32_bf16 v[146:149], v[106:109], v[202:205], 0
	v_mfma_f32_16x16x32_bf16 v[46:49], v[128:131], v[202:205], 0
	v_mfma_f32_16x16x32_bf16 v[102:105], v[106:109], v[210:213], 0
	v_mfma_f32_16x16x32_bf16 v[54:57], v[128:131], v[210:213], 0
	v_mfma_f32_16x16x32_bf16 v[124:127], v[110:113], v[174:177], v[124:127]
	v_mfma_f32_16x16x32_bf16 v[98:101], v[132:135], v[174:177], v[98:101]
	v_mfma_f32_16x16x32_bf16 v[154:157], v[110:113], v[198:201], v[154:157]
	v_mfma_f32_16x16x32_bf16 v[58:61], v[132:135], v[198:201], v[58:61]
	v_mfma_f32_16x16x32_bf16 v[146:149], v[110:113], v[206:209], v[146:149]
	v_mfma_f32_16x16x32_bf16 v[46:49], v[132:135], v[206:209], v[46:49]
	v_mfma_f32_16x16x32_bf16 v[102:105], v[110:113], v[214:217], v[102:105]
	v_mfma_f32_16x16x32_bf16 v[54:57], v[132:135], v[214:217], v[54:57]
	v_mfma_f32_16x16x32_bf16 v[120:123], v[136:139], v[170:173], 0
	v_mfma_f32_16x16x32_bf16 v[94:97], v[162:165], v[170:173], 0
	v_mfma_f32_16x16x32_bf16 v[150:153], v[136:139], v[178:181], 0
	v_mfma_f32_16x16x32_bf16 v[50:53], v[162:165], v[178:181], 0
	v_mfma_f32_16x16x32_bf16 v[140:143], v[136:139], v[202:205], 0
	v_mfma_f32_16x16x32_bf16 v[42:45], v[162:165], v[202:205], 0
	v_mfma_f32_16x16x32_bf16 v[114:117], v[136:139], v[210:213], 0
	v_mfma_f32_16x16x32_bf16 v[38:41], v[162:165], v[210:213], 0
	v_mfma_f32_16x16x32_bf16 v[120:123], v[158:161], v[174:177], v[120:123]
	v_mfma_f32_16x16x32_bf16 v[94:97], v[166:169], v[174:177], v[94:97]
	v_mfma_f32_16x16x32_bf16 v[150:153], v[158:161], v[198:201], v[150:153]
	v_mfma_f32_16x16x32_bf16 v[50:53], v[166:169], v[198:201], v[50:53]
	v_mfma_f32_16x16x32_bf16 v[140:143], v[158:161], v[206:209], v[140:143]
	v_mfma_f32_16x16x32_bf16 v[42:45], v[166:169], v[206:209], v[42:45]
	v_mfma_f32_16x16x32_bf16 v[114:117], v[158:161], v[214:217], v[114:117]
	v_mfma_f32_16x16x32_bf16 v[38:41], v[166:169], v[214:217], v[38:41]
	s_setprio 0
	s_barrier
	s_add_i32 s76, s76, s42
	s_mov_b32 m0, s76
	ds_read_b128 v[170:173], v234 offset:16384
	ds_read_b128 v[174:177], v234 offset:17408
	ds_read_b128 v[178:181], v234 offset:18432
	ds_read_b128 v[198:201], v234 offset:19456
	ds_read_b128 v[202:205], v234 offset:20480
	ds_read_b128 v[206:209], v234 offset:21504
	ds_read_b128 v[210:213], v234 offset:22528
	ds_read_b128 v[214:217], v234 offset:23552
	global_load_lds_dwordx4 v0, s[24:25]
	s_add_i32 m0, s76, 0x2000
	s_add_u32 s76, s24, 0x40000
	s_addc_u32 s77, s25, 0
	s_add_i32 vcc_hi, vcc_hi, s42
	global_load_lds_dwordx4 v192, s[24:25]
	s_mov_b32 m0, vcc_hi
	s_nop 0
	global_load_lds_dwordx4 v0, s[76:77]
	s_add_i32 m0, vcc_hi, 0x2000
	s_nop 0
	global_load_lds_dwordx4 v192, s[76:77]
	s_mov_b32 m0, s57
	s_nop 0
	global_load_lds_dwordx4 v188, s[28:29]
	s_mov_b32 m0, s66
	s_nop 0
	global_load_lds_dwordx4 v190, s[28:29]
	s_waitcnt vmcnt(8)
	s_waitcnt lgkmcnt(0)
	s_barrier
	s_setprio 1
	v_mfma_f32_16x16x32_bf16 v[86:89], v[106:109], v[170:173], 0
	v_mfma_f32_16x16x32_bf16 v[30:33], v[128:131], v[170:173], 0
	v_mfma_f32_16x16x32_bf16 v[78:81], v[106:109], v[178:181], 0
	v_mfma_f32_16x16x32_bf16 v[22:25], v[128:131], v[178:181], 0
	v_mfma_f32_16x16x32_bf16 v[70:73], v[106:109], v[202:205], 0
	v_mfma_f32_16x16x32_bf16 v[14:17], v[128:131], v[202:205], 0
	v_mfma_f32_16x16x32_bf16 v[90:93], v[106:109], v[210:213], 0
	v_mfma_f32_16x16x32_bf16 v[34:37], v[128:131], v[210:213], 0
	v_mfma_f32_16x16x32_bf16 v[86:89], v[110:113], v[174:177], v[86:89]
	v_mfma_f32_16x16x32_bf16 v[30:33], v[132:135], v[174:177], v[30:33]
	v_mfma_f32_16x16x32_bf16 v[78:81], v[110:113], v[198:201], v[78:81]
	v_mfma_f32_16x16x32_bf16 v[22:25], v[132:135], v[198:201], v[22:25]
	v_mfma_f32_16x16x32_bf16 v[70:73], v[110:113], v[206:209], v[70:73]
	v_mfma_f32_16x16x32_bf16 v[14:17], v[132:135], v[206:209], v[14:17]
	v_mfma_f32_16x16x32_bf16 v[90:93], v[110:113], v[214:217], v[90:93]
	v_mfma_f32_16x16x32_bf16 v[34:37], v[132:135], v[214:217], v[34:37]
	v_mfma_f32_16x16x32_bf16 v[82:85], v[136:139], v[170:173], 0
	v_mfma_f32_16x16x32_bf16 v[26:29], v[162:165], v[170:173], 0
	v_mfma_f32_16x16x32_bf16 v[74:77], v[136:139], v[178:181], 0
	v_mfma_f32_16x16x32_bf16 v[18:21], v[162:165], v[178:181], 0
	v_mfma_f32_16x16x32_bf16 v[66:69], v[136:139], v[202:205], 0
	v_mfma_f32_16x16x32_bf16 v[10:13], v[162:165], v[202:205], 0
	v_mfma_f32_16x16x32_bf16 v[62:65], v[136:139], v[210:213], 0
	v_mfma_f32_16x16x32_bf16 v[6:9], v[162:165], v[210:213], 0
	v_mfma_f32_16x16x32_bf16 v[82:85], v[158:161], v[174:177], v[82:85]
	v_mfma_f32_16x16x32_bf16 v[26:29], v[166:169], v[174:177], v[26:29]
	v_mfma_f32_16x16x32_bf16 v[74:77], v[158:161], v[198:201], v[74:77]
	v_mfma_f32_16x16x32_bf16 v[18:21], v[166:169], v[198:201], v[18:21]
	v_mfma_f32_16x16x32_bf16 v[66:69], v[158:161], v[206:209], v[66:69]
	v_mfma_f32_16x16x32_bf16 v[10:13], v[166:169], v[206:209], v[10:13]
	v_mfma_f32_16x16x32_bf16 v[62:65], v[158:161], v[214:217], v[62:65]
	v_mfma_f32_16x16x32_bf16 v[6:9], v[166:169], v[214:217], v[6:9]
	s_setprio 0
	s_barrier
	s_add_i32 s76, 0, 0x18000
	v_add_u32_e32 v118, s76, v220
	s_add_i32 s77, 0, 0x1c000
	ds_read_b128 v[106:109], v118
	ds_read_b128 v[110:113], v118 offset:1024
	ds_read_b128 v[128:131], v118 offset:2048
	ds_read_b128 v[132:135], v118 offset:3072
	v_add_u32_e32 v118, s77, v220
	ds_read_b128 v[136:139], v118
	ds_read_b128 v[158:161], v118 offset:1024
	ds_read_b128 v[162:165], v118 offset:2048
	ds_read_b128 v[166:169], v118 offset:3072
	s_add_u32 s28, s28, 0x40000
	s_addc_u32 s29, s29, 0
	s_mov_b32 m0, s67
	ds_read_b128 v[170:173], v234 offset:32768
	ds_read_b128 v[174:177], v234 offset:33792
	ds_read_b128 v[178:181], v234 offset:34816
	ds_read_b128 v[198:201], v234 offset:35840
	ds_read_b128 v[202:205], v234 offset:36864
	ds_read_b128 v[206:209], v234 offset:37888
	ds_read_b128 v[210:213], v234 offset:38912
	ds_read_b128 v[214:217], v234 offset:39936
	global_load_lds_dwordx4 v188, s[28:29]
	s_mov_b32 m0, s44
	s_nop 0
	global_load_lds_dwordx4 v190, s[28:29]
	s_waitcnt vmcnt(8)
	s_waitcnt lgkmcnt(0)
	s_barrier
	s_setprio 1
	v_mfma_f32_16x16x32_bf16 v[124:127], v[106:109], v[170:173], v[124:127]
	v_mfma_f32_16x16x32_bf16 v[98:101], v[128:131], v[170:173], v[98:101]
	v_mfma_f32_16x16x32_bf16 v[154:157], v[106:109], v[178:181], v[154:157]
	v_mfma_f32_16x16x32_bf16 v[58:61], v[128:131], v[178:181], v[58:61]
	v_mfma_f32_16x16x32_bf16 v[144:147], v[106:109], v[202:205], v[146:149]
	v_mfma_f32_16x16x32_bf16 v[46:49], v[128:131], v[202:205], v[46:49]
	v_mfma_f32_16x16x32_bf16 v[102:105], v[106:109], v[210:213], v[102:105]
	v_mfma_f32_16x16x32_bf16 v[54:57], v[128:131], v[210:213], v[54:57]
	v_mfma_f32_16x16x32_bf16 v[124:127], v[110:113], v[174:177], v[124:127]
	v_mfma_f32_16x16x32_bf16 v[98:101], v[132:135], v[174:177], v[98:101]
	v_mfma_f32_16x16x32_bf16 v[154:157], v[110:113], v[198:201], v[154:157]
	v_mfma_f32_16x16x32_bf16 v[58:61], v[132:135], v[198:201], v[58:61]
	v_mfma_f32_16x16x32_bf16 v[146:149], v[110:113], v[206:209], v[144:147]
	v_mfma_f32_16x16x32_bf16 v[46:49], v[132:135], v[206:209], v[46:49]
	v_mfma_f32_16x16x32_bf16 v[102:105], v[110:113], v[214:217], v[102:105]
	v_mfma_f32_16x16x32_bf16 v[54:57], v[132:135], v[214:217], v[54:57]
	v_mfma_f32_16x16x32_bf16 v[118:121], v[136:139], v[170:173], v[120:123]
	v_mfma_f32_16x16x32_bf16 v[94:97], v[162:165], v[170:173], v[94:97]
	v_mfma_f32_16x16x32_bf16 v[150:153], v[136:139], v[178:181], v[150:153]
	v_mfma_f32_16x16x32_bf16 v[50:53], v[162:165], v[178:181], v[50:53]
	v_mfma_f32_16x16x32_bf16 v[140:143], v[136:139], v[202:205], v[140:143]
	v_mfma_f32_16x16x32_bf16 v[42:45], v[162:165], v[202:205], v[42:45]
	v_mfma_f32_16x16x32_bf16 v[114:117], v[136:139], v[210:213], v[114:117]
	v_mfma_f32_16x16x32_bf16 v[38:41], v[162:165], v[210:213], v[38:41]
	v_mfma_f32_16x16x32_bf16 v[120:123], v[158:161], v[174:177], v[118:121]
	v_mfma_f32_16x16x32_bf16 v[94:97], v[166:169], v[174:177], v[94:97]
	v_mfma_f32_16x16x32_bf16 v[150:153], v[158:161], v[198:201], v[150:153]
	v_mfma_f32_16x16x32_bf16 v[50:53], v[166:169], v[198:201], v[50:53]
	v_mfma_f32_16x16x32_bf16 v[142:145], v[158:161], v[206:209], v[140:143]
	v_mfma_f32_16x16x32_bf16 v[42:45], v[166:169], v[206:209], v[42:45]
	v_mfma_f32_16x16x32_bf16 v[116:119], v[158:161], v[214:217], v[114:117]
	v_mfma_f32_16x16x32_bf16 v[38:41], v[166:169], v[214:217], v[38:41]
	s_setprio 0
	s_barrier
	s_add_i32 s100, s76, s42
	s_mov_b32 m0, s100
	ds_read_b128 v[170:173], v234 offset:49152
	ds_read_b128 v[174:177], v234 offset:50176
	ds_read_b128 v[178:181], v234 offset:51200
	ds_read_b128 v[198:201], v234 offset:52224
	ds_read_b128 v[202:205], v234 offset:53248
	ds_read_b128 v[206:209], v234 offset:54272
	ds_read_b128 v[210:213], v234 offset:55296
	ds_read_b128 v[214:217], v234 offset:56320
	s_add_u32 s24, s24, 0x80
	s_addc_u32 s25, s25, 0
	global_load_lds_dwordx4 v0, s[24:25]
	s_add_i32 m0, s100, 0x2000
	s_add_i32 s100, s77, s42
	global_load_lds_dwordx4 v192, s[24:25]
	s_add_u32 s24, s24, 0x40000
	s_addc_u32 s25, s25, 0
	s_mov_b32 m0, s100
	s_add_i32 s100, s100, 0x2000
	global_load_lds_dwordx4 v0, s[24:25]
	s_mov_b32 m0, s100
	s_add_u32 s28, s28, 0xfffc0080
	s_addc_u32 s29, s29, -1
	global_load_lds_dwordx4 v192, s[24:25]
	s_mov_b32 m0, s45
	s_nop 0
	global_load_lds_dwordx4 v188, s[28:29]
	s_mov_b32 m0, s70
	s_nop 0
	global_load_lds_dwordx4 v190, s[28:29]
	s_waitcnt vmcnt(8)
	s_waitcnt lgkmcnt(0)
	s_barrier
	s_setprio 1
	v_mfma_f32_16x16x32_bf16 v[86:89], v[106:109], v[170:173], v[86:89]
	v_mfma_f32_16x16x32_bf16 v[30:33], v[128:131], v[170:173], v[30:33]
	v_mfma_f32_16x16x32_bf16 v[78:81], v[106:109], v[178:181], v[78:81]
	v_mfma_f32_16x16x32_bf16 v[22:25], v[128:131], v[178:181], v[22:25]
	v_mfma_f32_16x16x32_bf16 v[70:73], v[106:109], v[202:205], v[70:73]
	v_mfma_f32_16x16x32_bf16 v[14:17], v[128:131], v[202:205], v[14:17]
	v_mfma_f32_16x16x32_bf16 v[90:93], v[106:109], v[210:213], v[90:93]
	v_mfma_f32_16x16x32_bf16 v[34:37], v[128:131], v[210:213], v[34:37]
	v_mfma_f32_16x16x32_bf16 v[86:89], v[110:113], v[174:177], v[86:89]
	v_mfma_f32_16x16x32_bf16 v[30:33], v[132:135], v[174:177], v[30:33]
	v_mfma_f32_16x16x32_bf16 v[78:81], v[110:113], v[198:201], v[78:81]
	v_mfma_f32_16x16x32_bf16 v[22:25], v[132:135], v[198:201], v[22:25]
	v_mfma_f32_16x16x32_bf16 v[70:73], v[110:113], v[206:209], v[70:73]
	v_mfma_f32_16x16x32_bf16 v[14:17], v[132:135], v[206:209], v[14:17]
	v_mfma_f32_16x16x32_bf16 v[90:93], v[110:113], v[214:217], v[90:93]
	v_mfma_f32_16x16x32_bf16 v[34:37], v[132:135], v[214:217], v[34:37]
	v_mfma_f32_16x16x32_bf16 v[82:85], v[136:139], v[170:173], v[82:85]
	v_mfma_f32_16x16x32_bf16 v[26:29], v[162:165], v[170:173], v[26:29]
	v_mfma_f32_16x16x32_bf16 v[74:77], v[136:139], v[178:181], v[74:77]
	v_mfma_f32_16x16x32_bf16 v[18:21], v[162:165], v[178:181], v[18:21]
	v_mfma_f32_16x16x32_bf16 v[66:69], v[136:139], v[202:205], v[66:69]
	v_mfma_f32_16x16x32_bf16 v[10:13], v[162:165], v[202:205], v[10:13]
	v_mfma_f32_16x16x32_bf16 v[62:65], v[136:139], v[210:213], v[62:65]
	v_mfma_f32_16x16x32_bf16 v[6:9], v[162:165], v[210:213], v[6:9]
	v_mfma_f32_16x16x32_bf16 v[82:85], v[158:161], v[174:177], v[82:85]
	v_mfma_f32_16x16x32_bf16 v[26:29], v[166:169], v[174:177], v[26:29]
	v_mfma_f32_16x16x32_bf16 v[74:77], v[158:161], v[198:201], v[74:77]
	v_mfma_f32_16x16x32_bf16 v[18:21], v[166:169], v[198:201], v[18:21]
	v_mfma_f32_16x16x32_bf16 v[66:69], v[158:161], v[206:209], v[66:69]
	v_mfma_f32_16x16x32_bf16 v[10:13], v[166:169], v[206:209], v[10:13]
	v_mfma_f32_16x16x32_bf16 v[62:65], v[158:161], v[214:217], v[62:65]
	v_mfma_f32_16x16x32_bf16 v[6:9], v[166:169], v[214:217], v[6:9]
	s_setprio 0
	s_barrier
	s_add_i32 vcc_lo, vcc_lo, 2
	s_add_u32 s22, s22, 0x100
	s_addc_u32 s23, s23, 0
	s_add_u32 s81, s81, 0x100
	s_addc_u32 s99, s99, 0
	s_cmp_gt_u32 vcc_lo, 13
	s_cbranch_scc0 .LBB0_453

.LBB0_710:
	s_ashr_i32 s25, s24, 31
	s_lshl_b64 s[12:13], s[24:25], 11
	s_cmp_eq_u32 s98, 0
	s_cselect_b32 s27, s46, s55
	s_cselect_b32 s25, s47, s57
	s_cselect_b32 s44, s89, s46
	s_cselect_b32 s45, s97, s47
	s_add_u32 s30, s27, s12
	s_addc_u32 s31, s25, s13
	s_and_b64 s[12:13], s[6:7], exec
	s_cselect_b32 s25, s31, s11
	s_cselect_b32 s27, s30, s10
	s_ashr_i32 s29, s28, 31
	s_lshl_b64 s[12:13], s[28:29], 11
	s_add_u32 s92, s44, s12
	s_addc_u32 s93, s45, s13
	s_and_b64 s[12:13], s[6:7], exec
	s_cselect_b32 s29, s93, s9
	s_cselect_b32 s44, s92, s8
	s_add_u32 s10, s10, 0x40080
	s_addc_u32 s11, s11, 0
	s_add_u32 s45, s8, 0x100
	s_addc_u32 s50, s9, 0
	s_mov_b32 s51, -2
	s_add_u32 s8, s10, 0xfffc0080
	s_addc_u32 s9, s11, -1
	s_add_i32 s67, 0, 0x10000
	s_cmp_eq_u32 s51, 12
	s_cselect_b32 s13, s25, s9
	s_cselect_b32 s12, s27, s8
	s_cselect_b32 s9, s29, s50
	s_cselect_b32 s8, s44, s45
	s_add_i32 s72, 0, 0x14000
	v_add_u32_e32 v146, s67, v245
	v_add_u32_e32 v162, s72, v245
	ds_read_b128 v[134:137], v146
	ds_read_b128 v[138:141], v146 offset:1024
	ds_read_b128 v[142:145], v146 offset:2048
	ds_read_b128 v[146:149], v146 offset:3072
	ds_read_b128 v[150:153], v162
	ds_read_b128 v[154:157], v162 offset:1024
	ds_read_b128 v[158:161], v162 offset:2048
	ds_read_b128 v[162:165], v162 offset:3072
	s_add_i32 m0, s68, 0xc000
	ds_read_b128 v[166:169], v247
	ds_read_b128 v[170:173], v247 offset:1024
	ds_read_b128 v[174:177], v247 offset:2048
	ds_read_b128 v[178:181], v247 offset:3072
	ds_read_b128 v[196:199], v247 offset:4096
	ds_read_b128 v[200:203], v247 offset:5120
	ds_read_b128 v[204:207], v247 offset:6144
	ds_read_b128 v[208:211], v247 offset:7168
	global_load_lds_dwordx4 v192, s[10:11]
	s_add_i32 m0, s68, 0xe000
	s_nop 0
	global_load_lds_dwordx4 v194, s[10:11]
	s_waitcnt vmcnt(8)
	s_waitcnt lgkmcnt(0)
	s_barrier
	s_setprio 1
	v_mfma_f32_16x16x32_bf16 v[130:133], v[134:137], v[166:169], 0
	v_mfma_f32_16x16x32_bf16 v[126:129], v[142:145], v[166:169], 0
	v_mfma_f32_16x16x32_bf16 v[114:117], v[134:137], v[174:177], 0
	v_mfma_f32_16x16x32_bf16 v[110:113], v[142:145], v[174:177], 0
	v_mfma_f32_16x16x32_bf16 v[98:101], v[134:137], v[196:199], 0
	v_mfma_f32_16x16x32_bf16 v[94:97], v[142:145], v[196:199], 0
	v_mfma_f32_16x16x32_bf16 v[82:85], v[134:137], v[204:207], 0
	v_mfma_f32_16x16x32_bf16 v[78:81], v[142:145], v[204:207], 0
	v_mfma_f32_16x16x32_bf16 v[130:133], v[138:141], v[170:173], v[130:133]
	v_mfma_f32_16x16x32_bf16 v[126:129], v[146:149], v[170:173], v[126:129]
	v_mfma_f32_16x16x32_bf16 v[114:117], v[138:141], v[178:181], v[114:117]
	v_mfma_f32_16x16x32_bf16 v[110:113], v[146:149], v[178:181], v[110:113]
	v_mfma_f32_16x16x32_bf16 v[98:101], v[138:141], v[200:203], v[98:101]
	v_mfma_f32_16x16x32_bf16 v[94:97], v[146:149], v[200:203], v[94:97]
	v_mfma_f32_16x16x32_bf16 v[82:85], v[138:141], v[208:211], v[82:85]
	v_mfma_f32_16x16x32_bf16 v[78:81], v[146:149], v[208:211], v[78:81]
	v_mfma_f32_16x16x32_bf16 v[122:125], v[150:153], v[166:169], 0
	v_mfma_f32_16x16x32_bf16 v[118:121], v[158:161], v[166:169], 0
	v_mfma_f32_16x16x32_bf16 v[106:109], v[150:153], v[174:177], 0
	v_mfma_f32_16x16x32_bf16 v[102:105], v[158:161], v[174:177], 0
	v_mfma_f32_16x16x32_bf16 v[90:93], v[150:153], v[196:199], 0
	v_mfma_f32_16x16x32_bf16 v[86:89], v[158:161], v[196:199], 0
	v_mfma_f32_16x16x32_bf16 v[74:77], v[150:153], v[204:207], 0
	v_mfma_f32_16x16x32_bf16 v[70:73], v[158:161], v[204:207], 0
	v_mfma_f32_16x16x32_bf16 v[122:125], v[154:157], v[170:173], v[122:125]
	v_mfma_f32_16x16x32_bf16 v[118:121], v[162:165], v[170:173], v[118:121]
	v_mfma_f32_16x16x32_bf16 v[106:109], v[154:157], v[178:181], v[106:109]
	v_mfma_f32_16x16x32_bf16 v[102:105], v[162:165], v[178:181], v[102:105]
	v_mfma_f32_16x16x32_bf16 v[90:93], v[154:157], v[200:203], v[90:93]
	v_mfma_f32_16x16x32_bf16 v[86:89], v[162:165], v[200:203], v[86:89]
	v_mfma_f32_16x16x32_bf16 v[74:77], v[154:157], v[208:211], v[74:77]
	v_mfma_f32_16x16x32_bf16 v[70:73], v[162:165], v[208:211], v[70:73]
	s_setprio 0
	s_barrier
	s_add_i32 s67, s67, s63
	s_mov_b32 m0, s67
	ds_read_b128 v[166:169], v247 offset:16384
	ds_read_b128 v[170:173], v247 offset:17408
	ds_read_b128 v[174:177], v247 offset:18432
	ds_read_b128 v[178:181], v247 offset:19456
	ds_read_b128 v[196:199], v247 offset:20480
	ds_read_b128 v[200:203], v247 offset:21504
	ds_read_b128 v[204:207], v247 offset:22528
	ds_read_b128 v[208:211], v247 offset:23552
	global_load_lds_dwordx4 v0, s[8:9]
	s_add_i32 m0, s67, 0x2000
	s_add_u32 s70, s8, 0x40000
	s_addc_u32 s71, s9, 0
	s_add_i32 s67, s72, s63
	global_load_lds_dwordx4 v190, s[8:9]
	s_mov_b32 m0, s67
	s_nop 0
	global_load_lds_dwordx4 v0, s[70:71]
	s_add_i32 m0, s67, 0x2000
	s_nop 0
	global_load_lds_dwordx4 v190, s[70:71]
	s_mov_b32 m0, s68
	s_nop 0
	global_load_lds_dwordx4 v182, s[12:13]
	s_mov_b32 m0, s69
	s_nop 0
	global_load_lds_dwordx4 v188, s[12:13]
	s_waitcnt vmcnt(8)
	s_waitcnt lgkmcnt(0)
	s_barrier
	s_setprio 1
	v_mfma_f32_16x16x32_bf16 v[66:69], v[134:137], v[166:169], 0
	v_mfma_f32_16x16x32_bf16 v[62:65], v[142:145], v[166:169], 0
	v_mfma_f32_16x16x32_bf16 v[50:53], v[134:137], v[174:177], 0
	v_mfma_f32_16x16x32_bf16 v[46:49], v[142:145], v[174:177], 0
	v_mfma_f32_16x16x32_bf16 v[34:37], v[134:137], v[196:199], 0
	v_mfma_f32_16x16x32_bf16 v[30:33], v[142:145], v[196:199], 0
	v_mfma_f32_16x16x32_bf16 v[18:21], v[134:137], v[204:207], 0
	v_mfma_f32_16x16x32_bf16 v[14:17], v[142:145], v[204:207], 0
	v_mfma_f32_16x16x32_bf16 v[66:69], v[138:141], v[170:173], v[66:69]
	v_mfma_f32_16x16x32_bf16 v[62:65], v[146:149], v[170:173], v[62:65]
	v_mfma_f32_16x16x32_bf16 v[50:53], v[138:141], v[178:181], v[50:53]
	v_mfma_f32_16x16x32_bf16 v[46:49], v[146:149], v[178:181], v[46:49]
	v_mfma_f32_16x16x32_bf16 v[34:37], v[138:141], v[200:203], v[34:37]
	v_mfma_f32_16x16x32_bf16 v[30:33], v[146:149], v[200:203], v[30:33]
	v_mfma_f32_16x16x32_bf16 v[18:21], v[138:141], v[208:211], v[18:21]
	v_mfma_f32_16x16x32_bf16 v[14:17], v[146:149], v[208:211], v[14:17]
	v_mfma_f32_16x16x32_bf16 v[58:61], v[150:153], v[166:169], 0
	v_mfma_f32_16x16x32_bf16 v[54:57], v[158:161], v[166:169], 0
	v_mfma_f32_16x16x32_bf16 v[42:45], v[150:153], v[174:177], 0
	v_mfma_f32_16x16x32_bf16 v[38:41], v[158:161], v[174:177], 0
	v_mfma_f32_16x16x32_bf16 v[26:29], v[150:153], v[196:199], 0
	v_mfma_f32_16x16x32_bf16 v[22:25], v[158:161], v[196:199], 0
	v_mfma_f32_16x16x32_bf16 v[10:13], v[150:153], v[204:207], 0
	v_mfma_f32_16x16x32_bf16 v[6:9], v[158:161], v[204:207], 0
	v_mfma_f32_16x16x32_bf16 v[58:61], v[154:157], v[170:173], v[58:61]
	v_mfma_f32_16x16x32_bf16 v[54:57], v[162:165], v[170:173], v[54:57]
	v_mfma_f32_16x16x32_bf16 v[42:45], v[154:157], v[178:181], v[42:45]
	v_mfma_f32_16x16x32_bf16 v[38:41], v[162:165], v[178:181], v[38:41]
	v_mfma_f32_16x16x32_bf16 v[26:29], v[154:157], v[200:203], v[26:29]
	v_mfma_f32_16x16x32_bf16 v[22:25], v[162:165], v[200:203], v[22:25]
	v_mfma_f32_16x16x32_bf16 v[10:13], v[154:157], v[208:211], v[10:13]
	v_mfma_f32_16x16x32_bf16 v[6:9], v[162:165], v[208:211], v[6:9]
	s_setprio 0
	s_barrier
	s_add_i32 s67, 0, 0x18000
	s_add_i32 s70, 0, 0x1c000
	v_add_u32_e32 v146, s67, v245
	v_add_u32_e32 v162, s70, v245
	ds_read_b128 v[134:137], v146
	ds_read_b128 v[138:141], v146 offset:1024
	ds_read_b128 v[142:145], v146 offset:2048
	ds_read_b128 v[146:149], v146 offset:3072
	ds_read_b128 v[150:153], v162
	ds_read_b128 v[154:157], v162 offset:1024
	ds_read_b128 v[158:161], v162 offset:2048
	ds_read_b128 v[162:165], v162 offset:3072
	s_add_u32 s12, s12, 0x40000
	s_addc_u32 s13, s13, 0
	s_mov_b32 m0, s78
	ds_read_b128 v[166:169], v247 offset:32768
	ds_read_b128 v[170:173], v247 offset:33792
	ds_read_b128 v[174:177], v247 offset:34816
	ds_read_b128 v[178:181], v247 offset:35840
	ds_read_b128 v[196:199], v247 offset:36864
	ds_read_b128 v[200:203], v247 offset:37888
	ds_read_b128 v[204:207], v247 offset:38912
	ds_read_b128 v[208:211], v247 offset:39936
	global_load_lds_dwordx4 v182, s[12:13]
	s_mov_b32 m0, s79
	s_nop 0
	global_load_lds_dwordx4 v188, s[12:13]
	s_waitcnt vmcnt(8)
	s_waitcnt lgkmcnt(0)
	s_barrier
	s_setprio 1
	v_mfma_f32_16x16x32_bf16 v[130:133], v[134:137], v[166:169], v[130:133]
	v_mfma_f32_16x16x32_bf16 v[126:129], v[142:145], v[166:169], v[126:129]
	v_mfma_f32_16x16x32_bf16 v[114:117], v[134:137], v[174:177], v[114:117]
	v_mfma_f32_16x16x32_bf16 v[110:113], v[142:145], v[174:177], v[110:113]
	v_mfma_f32_16x16x32_bf16 v[98:101], v[134:137], v[196:199], v[98:101]
	v_mfma_f32_16x16x32_bf16 v[94:97], v[142:145], v[196:199], v[94:97]
	v_mfma_f32_16x16x32_bf16 v[82:85], v[134:137], v[204:207], v[82:85]
	v_mfma_f32_16x16x32_bf16 v[78:81], v[142:145], v[204:207], v[78:81]
	v_mfma_f32_16x16x32_bf16 v[130:133], v[138:141], v[170:173], v[130:133]
	v_mfma_f32_16x16x32_bf16 v[126:129], v[146:149], v[170:173], v[126:129]
	v_mfma_f32_16x16x32_bf16 v[114:117], v[138:141], v[178:181], v[114:117]
	v_mfma_f32_16x16x32_bf16 v[110:113], v[146:149], v[178:181], v[110:113]
	v_mfma_f32_16x16x32_bf16 v[98:101], v[138:141], v[200:203], v[98:101]
	v_mfma_f32_16x16x32_bf16 v[94:97], v[146:149], v[200:203], v[94:97]
	v_mfma_f32_16x16x32_bf16 v[82:85], v[138:141], v[208:211], v[82:85]
	v_mfma_f32_16x16x32_bf16 v[78:81], v[146:149], v[208:211], v[78:81]
	v_mfma_f32_16x16x32_bf16 v[122:125], v[150:153], v[166:169], v[122:125]
	v_mfma_f32_16x16x32_bf16 v[118:121], v[158:161], v[166:169], v[118:121]
	v_mfma_f32_16x16x32_bf16 v[106:109], v[150:153], v[174:177], v[106:109]
	v_mfma_f32_16x16x32_bf16 v[102:105], v[158:161], v[174:177], v[102:105]
	v_mfma_f32_16x16x32_bf16 v[90:93], v[150:153], v[196:199], v[90:93]
	v_mfma_f32_16x16x32_bf16 v[86:89], v[158:161], v[196:199], v[86:89]
	v_mfma_f32_16x16x32_bf16 v[74:77], v[150:153], v[204:207], v[74:77]
	v_mfma_f32_16x16x32_bf16 v[70:73], v[158:161], v[204:207], v[70:73]
	v_mfma_f32_16x16x32_bf16 v[122:125], v[154:157], v[170:173], v[122:125]
	v_mfma_f32_16x16x32_bf16 v[118:121], v[162:165], v[170:173], v[118:121]
	v_mfma_f32_16x16x32_bf16 v[106:109], v[154:157], v[178:181], v[106:109]
	v_mfma_f32_16x16x32_bf16 v[102:105], v[162:165], v[178:181], v[102:105]
	v_mfma_f32_16x16x32_bf16 v[90:93], v[154:157], v[200:203], v[90:93]
	v_mfma_f32_16x16x32_bf16 v[86:89], v[162:165], v[200:203], v[86:89]
	v_mfma_f32_16x16x32_bf16 v[74:77], v[154:157], v[208:211], v[74:77]
	v_mfma_f32_16x16x32_bf16 v[70:73], v[162:165], v[208:211], v[70:73]
	s_setprio 0
	s_barrier
	s_add_i32 s100, s67, s63
	s_mov_b32 m0, s100
	ds_read_b128 v[166:169], v247 offset:49152
	ds_read_b128 v[170:173], v247 offset:50176
	ds_read_b128 v[174:177], v247 offset:51200
	ds_read_b128 v[178:181], v247 offset:52224
	ds_read_b128 v[196:199], v247 offset:53248
	ds_read_b128 v[200:203], v247 offset:54272
	ds_read_b128 v[204:207], v247 offset:55296
	ds_read_b128 v[208:211], v247 offset:56320
	s_add_u32 s8, s8, 0x80
	s_addc_u32 s9, s9, 0
	global_load_lds_dwordx4 v0, s[8:9]
	s_add_i32 m0, s100, 0x2000
	s_add_i32 s100, s70, s63
	global_load_lds_dwordx4 v190, s[8:9]
	s_add_u32 s8, s8, 0x40000
	s_addc_u32 s9, s9, 0
	s_mov_b32 m0, s100
	s_add_i32 s100, s100, 0x2000
	global_load_lds_dwordx4 v0, s[8:9]
	s_mov_b32 m0, s100
	s_add_u32 s12, s12, 0xfffc0080
	s_addc_u32 s13, s13, -1
	global_load_lds_dwordx4 v190, s[8:9]
	s_mov_b32 m0, s80
	s_nop 0
	global_load_lds_dwordx4 v182, s[12:13]
	s_mov_b32 m0, s81
	s_nop 0
	global_load_lds_dwordx4 v188, s[12:13]
	s_waitcnt vmcnt(8)
	s_waitcnt lgkmcnt(0)
	s_barrier
	s_setprio 1
	v_mfma_f32_16x16x32_bf16 v[66:69], v[134:137], v[166:169], v[66:69]
	v_mfma_f32_16x16x32_bf16 v[62:65], v[142:145], v[166:169], v[62:65]
	v_mfma_f32_16x16x32_bf16 v[50:53], v[134:137], v[174:177], v[50:53]
	v_mfma_f32_16x16x32_bf16 v[46:49], v[142:145], v[174:177], v[46:49]
	v_mfma_f32_16x16x32_bf16 v[34:37], v[134:137], v[196:199], v[34:37]
	v_mfma_f32_16x16x32_bf16 v[30:33], v[142:145], v[196:199], v[30:33]
	v_mfma_f32_16x16x32_bf16 v[18:21], v[134:137], v[204:207], v[18:21]
	v_mfma_f32_16x16x32_bf16 v[14:17], v[142:145], v[204:207], v[14:17]
	v_mfma_f32_16x16x32_bf16 v[66:69], v[138:141], v[170:173], v[66:69]
	v_mfma_f32_16x16x32_bf16 v[62:65], v[146:149], v[170:173], v[62:65]
	v_mfma_f32_16x16x32_bf16 v[50:53], v[138:141], v[178:181], v[50:53]
	v_mfma_f32_16x16x32_bf16 v[46:49], v[146:149], v[178:181], v[46:49]
	v_mfma_f32_16x16x32_bf16 v[34:37], v[138:141], v[200:203], v[34:37]
	v_mfma_f32_16x16x32_bf16 v[30:33], v[146:149], v[200:203], v[30:33]
	v_mfma_f32_16x16x32_bf16 v[18:21], v[138:141], v[208:211], v[18:21]
	v_mfma_f32_16x16x32_bf16 v[14:17], v[146:149], v[208:211], v[14:17]
	v_mfma_f32_16x16x32_bf16 v[58:61], v[150:153], v[166:169], v[58:61]
	v_mfma_f32_16x16x32_bf16 v[54:57], v[158:161], v[166:169], v[54:57]
	v_mfma_f32_16x16x32_bf16 v[42:45], v[150:153], v[174:177], v[42:45]
	v_mfma_f32_16x16x32_bf16 v[38:41], v[158:161], v[174:177], v[38:41]
	v_mfma_f32_16x16x32_bf16 v[26:29], v[150:153], v[196:199], v[26:29]
	v_mfma_f32_16x16x32_bf16 v[22:25], v[158:161], v[196:199], v[22:25]
	v_mfma_f32_16x16x32_bf16 v[10:13], v[150:153], v[204:207], v[10:13]
	v_mfma_f32_16x16x32_bf16 v[6:9], v[158:161], v[204:207], v[6:9]
	v_mfma_f32_16x16x32_bf16 v[58:61], v[154:157], v[170:173], v[58:61]
	v_mfma_f32_16x16x32_bf16 v[54:57], v[162:165], v[170:173], v[54:57]
	v_mfma_f32_16x16x32_bf16 v[42:45], v[154:157], v[178:181], v[42:45]
	v_mfma_f32_16x16x32_bf16 v[38:41], v[162:165], v[178:181], v[38:41]
	v_mfma_f32_16x16x32_bf16 v[26:29], v[154:157], v[200:203], v[26:29]
	v_mfma_f32_16x16x32_bf16 v[22:25], v[162:165], v[200:203], v[22:25]
	v_mfma_f32_16x16x32_bf16 v[10:13], v[154:157], v[208:211], v[10:13]
	v_mfma_f32_16x16x32_bf16 v[6:9], v[162:165], v[208:211], v[6:9]
	s_setprio 0
	s_barrier
	s_add_i32 s51, s51, 2
	s_add_u32 s10, s10, 0x100
	s_addc_u32 s11, s11, 0
	s_add_u32 s45, s45, 0x100
	s_addc_u32 s50, s50, 0
	s_cmp_gt_u32 s51, 13
	s_cbranch_scc0 .LBB0_711

.LBB0_1064:
	s_add_u32 s10, s30, 0x80
	s_addc_u32 s11, s31, 0
	s_add_u32 s30, s26, 0x100
	s_addc_u32 s31, s27, 0
	s_mov_b32 s26, 0
	s_add_i32 s44, s26, 2
	s_add_u32 s45, s10, 0x80
	s_addc_u32 s27, s11, 0
	s_add_i32 s72, 0, 0x10000
	s_cmp_eq_u32 s68, s26
	s_cselect_b32 s27, s25, s27
	s_cselect_b32 s26, s24, s45
	s_cselect_b32 s71, s29, s31
	s_cselect_b32 s70, s28, s30
	s_add_i32 s45, 0, 0x14000
	v_add_u32_e32 v114, s72, v217
	v_add_u32_e32 v162, s45, v217
	ds_read_b128 v[94:97], v114
	ds_read_b128 v[102:105], v114 offset:1024
	ds_read_b128 v[110:113], v114 offset:2048
	ds_read_b128 v[114:117], v114 offset:3072
	ds_read_b128 v[150:153], v162
	ds_read_b128 v[154:157], v162 offset:1024
	ds_read_b128 v[158:161], v162 offset:2048
	ds_read_b128 v[162:165], v162 offset:3072
	s_add_i32 m0, s57, 0xc000
	ds_read_b128 v[166:169], v236
	ds_read_b128 v[170:173], v236 offset:1024
	ds_read_b128 v[174:177], v236 offset:2048
	ds_read_b128 v[178:181], v236 offset:3072
	ds_read_b128 v[196:199], v236 offset:4096
	ds_read_b128 v[200:203], v236 offset:5120
	ds_read_b128 v[204:207], v236 offset:6144
	ds_read_b128 v[208:211], v236 offset:7168
	global_load_lds_dwordx4 v192, s[10:11]
	s_add_i32 m0, s57, 0xe000
	s_nop 0
	global_load_lds_dwordx4 v194, s[10:11]
	s_waitcnt vmcnt(8)
	s_waitcnt lgkmcnt(0)
	s_barrier
	s_setprio 1
	v_mfma_f32_16x16x32_bf16 v[146:149], v[94:97], v[166:169], 0
	v_mfma_f32_16x16x32_bf16 v[142:145], v[110:113], v[166:169], 0
	v_mfma_f32_16x16x32_bf16 v[130:133], v[94:97], v[174:177], 0
	v_mfma_f32_16x16x32_bf16 v[126:129], v[110:113], v[174:177], 0
	v_mfma_f32_16x16x32_bf16 v[106:109], v[94:97], v[196:199], 0
	v_mfma_f32_16x16x32_bf16 v[98:101], v[110:113], v[196:199], 0
	v_mfma_f32_16x16x32_bf16 v[82:85], v[94:97], v[204:207], 0
	v_mfma_f32_16x16x32_bf16 v[78:81], v[110:113], v[204:207], 0
	v_mfma_f32_16x16x32_bf16 v[146:149], v[102:105], v[170:173], v[146:149]
	v_mfma_f32_16x16x32_bf16 v[142:145], v[114:117], v[170:173], v[142:145]
	v_mfma_f32_16x16x32_bf16 v[130:133], v[102:105], v[178:181], v[130:133]
	v_mfma_f32_16x16x32_bf16 v[126:129], v[114:117], v[178:181], v[126:129]
	v_mfma_f32_16x16x32_bf16 v[106:109], v[102:105], v[200:203], v[106:109]
	v_mfma_f32_16x16x32_bf16 v[98:101], v[114:117], v[200:203], v[98:101]
	v_mfma_f32_16x16x32_bf16 v[82:85], v[102:105], v[208:211], v[82:85]
	v_mfma_f32_16x16x32_bf16 v[78:81], v[114:117], v[208:211], v[78:81]
	v_mfma_f32_16x16x32_bf16 v[138:141], v[150:153], v[166:169], 0
	v_mfma_f32_16x16x32_bf16 v[134:137], v[158:161], v[166:169], 0
	v_mfma_f32_16x16x32_bf16 v[122:125], v[150:153], v[174:177], 0
	v_mfma_f32_16x16x32_bf16 v[118:121], v[158:161], v[174:177], 0
	v_mfma_f32_16x16x32_bf16 v[90:93], v[150:153], v[196:199], 0
	v_mfma_f32_16x16x32_bf16 v[86:89], v[158:161], v[196:199], 0
	v_mfma_f32_16x16x32_bf16 v[74:77], v[150:153], v[204:207], 0
	v_mfma_f32_16x16x32_bf16 v[70:73], v[158:161], v[204:207], 0
	v_mfma_f32_16x16x32_bf16 v[138:141], v[154:157], v[170:173], v[138:141]
	v_mfma_f32_16x16x32_bf16 v[134:137], v[162:165], v[170:173], v[134:137]
	v_mfma_f32_16x16x32_bf16 v[122:125], v[154:157], v[178:181], v[122:125]
	v_mfma_f32_16x16x32_bf16 v[118:121], v[162:165], v[178:181], v[118:121]
	v_mfma_f32_16x16x32_bf16 v[90:93], v[154:157], v[200:203], v[90:93]
	v_mfma_f32_16x16x32_bf16 v[86:89], v[162:165], v[200:203], v[86:89]
	v_mfma_f32_16x16x32_bf16 v[74:77], v[154:157], v[208:211], v[74:77]
	v_mfma_f32_16x16x32_bf16 v[70:73], v[162:165], v[208:211], v[70:73]
	s_setprio 0
	s_barrier
	s_add_i32 s72, s72, s54
	s_mov_b32 m0, s72
	ds_read_b128 v[166:169], v236 offset:16384
	ds_read_b128 v[170:173], v236 offset:17408
	ds_read_b128 v[174:177], v236 offset:18432
	ds_read_b128 v[178:181], v236 offset:19456
	ds_read_b128 v[196:199], v236 offset:20480
	ds_read_b128 v[200:203], v236 offset:21504
	ds_read_b128 v[204:207], v236 offset:22528
	ds_read_b128 v[208:211], v236 offset:23552
	global_load_lds_dwordx4 v0, s[70:71]
	s_add_i32 m0, s72, 0x2000
	s_add_u32 s100, s70, 0x80
	s_addc_u32 s101, s71, 0
	global_load_lds_dwordx4 v190, s[70:71]
	s_add_u32 s70, s70, s42
	s_addc_u32 s71, s71, 0
	s_add_i32 s45, s45, s54
	s_mov_b32 m0, s45
	s_nop 0
	global_load_lds_dwordx4 v0, s[70:71]
	s_add_i32 m0, s45, 0x2000
	s_nop 0
	global_load_lds_dwordx4 v190, s[70:71]
	s_mov_b32 m0, s57
	s_nop 0
	global_load_lds_dwordx4 v182, s[26:27]
	s_mov_b32 m0, s58
	s_nop 0
	global_load_lds_dwordx4 v188, s[26:27]
	s_waitcnt vmcnt(8)
	s_waitcnt lgkmcnt(0)
	s_barrier
	s_setprio 1
	v_mfma_f32_16x16x32_bf16 v[66:69], v[94:97], v[166:169], 0
	v_mfma_f32_16x16x32_bf16 v[62:65], v[110:113], v[166:169], 0
	v_mfma_f32_16x16x32_bf16 v[50:53], v[94:97], v[174:177], 0
	v_mfma_f32_16x16x32_bf16 v[46:49], v[110:113], v[174:177], 0
	v_mfma_f32_16x16x32_bf16 v[34:37], v[94:97], v[196:199], 0
	v_mfma_f32_16x16x32_bf16 v[30:33], v[110:113], v[196:199], 0
	v_mfma_f32_16x16x32_bf16 v[18:21], v[94:97], v[204:207], 0
	v_mfma_f32_16x16x32_bf16 v[14:17], v[110:113], v[204:207], 0
	v_mfma_f32_16x16x32_bf16 v[66:69], v[102:105], v[170:173], v[66:69]
	v_mfma_f32_16x16x32_bf16 v[62:65], v[114:117], v[170:173], v[62:65]
	v_mfma_f32_16x16x32_bf16 v[50:53], v[102:105], v[178:181], v[50:53]
	v_mfma_f32_16x16x32_bf16 v[46:49], v[114:117], v[178:181], v[46:49]
	v_mfma_f32_16x16x32_bf16 v[34:37], v[102:105], v[200:203], v[34:37]
	v_mfma_f32_16x16x32_bf16 v[30:33], v[114:117], v[200:203], v[30:33]
	v_mfma_f32_16x16x32_bf16 v[18:21], v[102:105], v[208:211], v[18:21]
	v_mfma_f32_16x16x32_bf16 v[14:17], v[114:117], v[208:211], v[14:17]
	v_mfma_f32_16x16x32_bf16 v[58:61], v[150:153], v[166:169], 0
	v_mfma_f32_16x16x32_bf16 v[54:57], v[158:161], v[166:169], 0
	v_mfma_f32_16x16x32_bf16 v[42:45], v[150:153], v[174:177], 0
	v_mfma_f32_16x16x32_bf16 v[38:41], v[158:161], v[174:177], 0
	v_mfma_f32_16x16x32_bf16 v[26:29], v[150:153], v[196:199], 0
	v_mfma_f32_16x16x32_bf16 v[22:25], v[158:161], v[196:199], 0
	v_mfma_f32_16x16x32_bf16 v[10:13], v[150:153], v[204:207], 0
	v_mfma_f32_16x16x32_bf16 v[6:9], v[158:161], v[204:207], 0
	v_mfma_f32_16x16x32_bf16 v[58:61], v[154:157], v[170:173], v[58:61]
	v_mfma_f32_16x16x32_bf16 v[54:57], v[162:165], v[170:173], v[54:57]
	v_mfma_f32_16x16x32_bf16 v[42:45], v[154:157], v[178:181], v[42:45]
	v_mfma_f32_16x16x32_bf16 v[38:41], v[162:165], v[178:181], v[38:41]
	v_mfma_f32_16x16x32_bf16 v[26:29], v[154:157], v[200:203], v[26:29]
	v_mfma_f32_16x16x32_bf16 v[22:25], v[162:165], v[200:203], v[22:25]
	v_mfma_f32_16x16x32_bf16 v[10:13], v[154:157], v[208:211], v[10:13]
	v_mfma_f32_16x16x32_bf16 v[6:9], v[162:165], v[208:211], v[6:9]
	s_setprio 0
	s_barrier
	s_add_i32 s45, 0, 0x18000
	v_add_u32_e32 v114, s45, v217
	v_add_u32_e32 v162, 0x1c000, v217
	ds_read_b128 v[94:97], v114
	ds_read_b128 v[102:105], v114 offset:1024
	ds_read_b128 v[110:113], v114 offset:2048
	ds_read_b128 v[114:117], v114 offset:3072
	ds_read_b128 v[150:153], v162
	ds_read_b128 v[154:157], v162 offset:1024
	ds_read_b128 v[158:161], v162 offset:2048
	ds_read_b128 v[162:165], v162 offset:3072
	s_add_u32 s26, s26, s42
	s_addc_u32 s27, s27, 0
	s_mov_b32 m0, s59
	ds_read_b128 v[166:169], v236 offset:32768
	ds_read_b128 v[170:173], v236 offset:33792
	ds_read_b128 v[174:177], v236 offset:34816
	ds_read_b128 v[178:181], v236 offset:35840
	ds_read_b128 v[196:199], v236 offset:36864
	ds_read_b128 v[200:203], v236 offset:37888
	ds_read_b128 v[204:207], v236 offset:38912
	ds_read_b128 v[208:211], v236 offset:39936
	global_load_lds_dwordx4 v182, s[26:27]
	s_mov_b32 m0, s62
	s_nop 0
	global_load_lds_dwordx4 v188, s[26:27]
	s_waitcnt vmcnt(8)
	s_waitcnt lgkmcnt(0)
	s_barrier
	s_setprio 1
	v_mfma_f32_16x16x32_bf16 v[146:149], v[94:97], v[166:169], v[146:149]
	v_mfma_f32_16x16x32_bf16 v[142:145], v[110:113], v[166:169], v[142:145]
	v_mfma_f32_16x16x32_bf16 v[130:133], v[94:97], v[174:177], v[130:133]
	v_mfma_f32_16x16x32_bf16 v[126:129], v[110:113], v[174:177], v[126:129]
	v_mfma_f32_16x16x32_bf16 v[106:109], v[94:97], v[196:199], v[106:109]
	v_mfma_f32_16x16x32_bf16 v[98:101], v[110:113], v[196:199], v[98:101]
	v_mfma_f32_16x16x32_bf16 v[82:85], v[94:97], v[204:207], v[82:85]
	v_mfma_f32_16x16x32_bf16 v[78:81], v[110:113], v[204:207], v[78:81]
	v_mfma_f32_16x16x32_bf16 v[146:149], v[102:105], v[170:173], v[146:149]
	v_mfma_f32_16x16x32_bf16 v[142:145], v[114:117], v[170:173], v[142:145]
	v_mfma_f32_16x16x32_bf16 v[130:133], v[102:105], v[178:181], v[130:133]
	v_mfma_f32_16x16x32_bf16 v[126:129], v[114:117], v[178:181], v[126:129]
	v_mfma_f32_16x16x32_bf16 v[106:109], v[102:105], v[200:203], v[106:109]
	v_mfma_f32_16x16x32_bf16 v[98:101], v[114:117], v[200:203], v[98:101]
	v_mfma_f32_16x16x32_bf16 v[82:85], v[102:105], v[208:211], v[82:85]
	v_mfma_f32_16x16x32_bf16 v[78:81], v[114:117], v[208:211], v[78:81]
	v_mfma_f32_16x16x32_bf16 v[138:141], v[150:153], v[166:169], v[138:141]
	v_mfma_f32_16x16x32_bf16 v[134:137], v[158:161], v[166:169], v[134:137]
	v_mfma_f32_16x16x32_bf16 v[122:125], v[150:153], v[174:177], v[122:125]
	v_mfma_f32_16x16x32_bf16 v[118:121], v[158:161], v[174:177], v[118:121]
	v_mfma_f32_16x16x32_bf16 v[90:93], v[150:153], v[196:199], v[90:93]
	v_mfma_f32_16x16x32_bf16 v[86:89], v[158:161], v[196:199], v[86:89]
	v_mfma_f32_16x16x32_bf16 v[74:77], v[150:153], v[204:207], v[74:77]
	v_mfma_f32_16x16x32_bf16 v[70:73], v[158:161], v[204:207], v[70:73]
	v_mfma_f32_16x16x32_bf16 v[138:141], v[154:157], v[170:173], v[138:141]
	v_mfma_f32_16x16x32_bf16 v[134:137], v[162:165], v[170:173], v[134:137]
	v_mfma_f32_16x16x32_bf16 v[122:125], v[154:157], v[178:181], v[122:125]
	v_mfma_f32_16x16x32_bf16 v[118:121], v[162:165], v[178:181], v[118:121]
	v_mfma_f32_16x16x32_bf16 v[90:93], v[154:157], v[200:203], v[90:93]
	v_mfma_f32_16x16x32_bf16 v[86:89], v[162:165], v[200:203], v[86:89]
	v_mfma_f32_16x16x32_bf16 v[74:77], v[154:157], v[208:211], v[74:77]
	v_mfma_f32_16x16x32_bf16 v[70:73], v[162:165], v[208:211], v[70:73]
	s_setprio 0
	s_barrier
	s_add_i32 s32, s45, s54
	s_mov_b32 m0, s32
	ds_read_b128 v[166:169], v236 offset:49152
	ds_read_b128 v[170:173], v236 offset:50176
	ds_read_b128 v[174:177], v236 offset:51200
	ds_read_b128 v[178:181], v236 offset:52224
	ds_read_b128 v[196:199], v236 offset:53248
	ds_read_b128 v[200:203], v236 offset:54272
	ds_read_b128 v[204:207], v236 offset:55296
	ds_read_b128 v[208:211], v236 offset:56320
	global_load_lds_dwordx4 v0, s[100:101]
	s_add_i32 m0, s32, 0x2000
	s_add_i32 s32, s54, 0x1c000
	global_load_lds_dwordx4 v190, s[100:101]
	s_add_u32 s70, s70, 0x80
	s_addc_u32 s71, s71, 0
	s_mov_b32 m0, s32
	s_add_i32 s32, s32, 0x2000
	global_load_lds_dwordx4 v0, s[70:71]
	s_mov_b32 m0, s32
	s_sub_u32 s26, s26, s42
	s_subb_u32 s27, s27, 0
	global_load_lds_dwordx4 v190, s[70:71]
	s_add_u32 s26, s26, 0x80
	s_addc_u32 s27, s27, 0
	s_mov_b32 m0, s63
	s_nop 0
	global_load_lds_dwordx4 v182, s[26:27]
	s_mov_b32 m0, s66
	s_nop 0
	global_load_lds_dwordx4 v188, s[26:27]
	s_waitcnt vmcnt(8)
	s_waitcnt lgkmcnt(0)
	s_barrier
	s_setprio 1
	v_mfma_f32_16x16x32_bf16 v[66:69], v[94:97], v[166:169], v[66:69]
	v_mfma_f32_16x16x32_bf16 v[62:65], v[110:113], v[166:169], v[62:65]
	v_mfma_f32_16x16x32_bf16 v[50:53], v[94:97], v[174:177], v[50:53]
	v_mfma_f32_16x16x32_bf16 v[46:49], v[110:113], v[174:177], v[46:49]
	v_mfma_f32_16x16x32_bf16 v[34:37], v[94:97], v[196:199], v[34:37]
	v_mfma_f32_16x16x32_bf16 v[30:33], v[110:113], v[196:199], v[30:33]
	v_mfma_f32_16x16x32_bf16 v[18:21], v[94:97], v[204:207], v[18:21]
	v_mfma_f32_16x16x32_bf16 v[14:17], v[110:113], v[204:207], v[14:17]
	v_mfma_f32_16x16x32_bf16 v[66:69], v[102:105], v[170:173], v[66:69]
	v_mfma_f32_16x16x32_bf16 v[62:65], v[114:117], v[170:173], v[62:65]
	v_mfma_f32_16x16x32_bf16 v[50:53], v[102:105], v[178:181], v[50:53]
	v_mfma_f32_16x16x32_bf16 v[46:49], v[114:117], v[178:181], v[46:49]
	v_mfma_f32_16x16x32_bf16 v[34:37], v[102:105], v[200:203], v[34:37]
	v_mfma_f32_16x16x32_bf16 v[30:33], v[114:117], v[200:203], v[30:33]
	v_mfma_f32_16x16x32_bf16 v[18:21], v[102:105], v[208:211], v[18:21]
	v_mfma_f32_16x16x32_bf16 v[14:17], v[114:117], v[208:211], v[14:17]
	v_mfma_f32_16x16x32_bf16 v[58:61], v[150:153], v[166:169], v[58:61]
	v_mfma_f32_16x16x32_bf16 v[54:57], v[158:161], v[166:169], v[54:57]
	v_mfma_f32_16x16x32_bf16 v[42:45], v[150:153], v[174:177], v[42:45]
	v_mfma_f32_16x16x32_bf16 v[38:41], v[158:161], v[174:177], v[38:41]
	v_mfma_f32_16x16x32_bf16 v[26:29], v[150:153], v[196:199], v[26:29]
	v_mfma_f32_16x16x32_bf16 v[22:25], v[158:161], v[196:199], v[22:25]
	v_mfma_f32_16x16x32_bf16 v[10:13], v[150:153], v[204:207], v[10:13]
	v_mfma_f32_16x16x32_bf16 v[6:9], v[158:161], v[204:207], v[6:9]
	v_mfma_f32_16x16x32_bf16 v[58:61], v[154:157], v[170:173], v[58:61]
	v_mfma_f32_16x16x32_bf16 v[54:57], v[162:165], v[170:173], v[54:57]
	v_mfma_f32_16x16x32_bf16 v[42:45], v[154:157], v[178:181], v[42:45]
	v_mfma_f32_16x16x32_bf16 v[38:41], v[162:165], v[178:181], v[38:41]
	v_mfma_f32_16x16x32_bf16 v[26:29], v[154:157], v[200:203], v[26:29]
	v_mfma_f32_16x16x32_bf16 v[22:25], v[162:165], v[200:203], v[22:25]
	v_mfma_f32_16x16x32_bf16 v[10:13], v[154:157], v[208:211], v[10:13]
	v_mfma_f32_16x16x32_bf16 v[6:9], v[162:165], v[208:211], v[6:9]
	s_setprio 0
	s_barrier
	s_add_u32 s10, s10, 0x100
	s_addc_u32 s11, s11, 0
	s_add_u32 s30, s30, 0x100
	s_addc_u32 s31, s31, 0
	s_cmp_ge_u32 s44, s67
	s_mov_b32 s26, s44
	s_cbranch_scc0 .LBB0_1065
